# attention prologue: q-norm gains fetched with one dword load per lane and broadcast within half-waves by ds_bpermute instead of eight 16-byte loads per lane
# baseline (speedup 1.0000x reference)
.LBB0_146:
	s_or_b64 exec, exec, s[44:45]
	s_ashr_i32 s3, s4, 1
	s_andn2_b32 s3, s3, 31
	v_and_b32_e32 v47, 31, v40
	s_add_i32 s3, s3, s11
	v_or_b32_e32 v202, s3, v47
	v_ashrrev_i32_e32 v203, 31, v202
	v_lshl_add_u64 v[0:1], v[202:203], 2, s[20:21]
	global_load_dword v237, v[0:1], off sc1
	v_lshl_add_u64 v[0:1], s[36:37], 0, v[202:203]
	v_readlane_b32 s14, v253, 43
	v_lshlrev_b64 v[0:1], 11, v[0:1]
	v_readlane_b32 s15, v253, 44
	v_bfe_u32 v45, v40, 5, 1
	s_lshl_b32 s36, s5, 1
	v_lshl_add_u64 v[0:1], s[14:15], 0, v[0:1]
	v_lshl_add_u64 v[200:201], v[0:1], 0, s[36:37]
	v_lshlrev_b32_e32 v49, 4, v45
	v_add_u32_e32 v0, v200, v49
	v_subrev_u32_e32 v4, s74, v0
	buffer_load_dwordx4 v[0:3], v4, s[76:79], 0 offen sc1
	buffer_load_dwordx4 v[36:39], v4, s[76:79], 0 offen offset:32 sc1
	buffer_load_dwordx4 v[74:77], v4, s[76:79], 0 offen offset:64 sc1
	buffer_load_dwordx4 v[62:65], v4, s[76:79], 0 offen offset:96 sc1
	v_and_b32_e32 v5, 64, v227
	v_xor_b32_e32 v4, 32, v227
	v_add_u32_e32 v51, 64, v5
	s_lshl_b32 s5, s5, 2
	v_cmp_lt_i32_e32 vcc, v4, v51
	s_add_u32 s14, s70, s5
	s_addc_u32 s15, s71, 0
	v_cndmask_b32_e32 v4, v227, v4, vcc
	v_lshlrev_b32_e32 v140, 2, v4
	v_lshrrev_b32_e32 v100, 3, v47
	v_and_b32_e32 v101, 7, v47
	v_lshlrev_b32_e32 v100, 6, v100
	v_lshl_or_b32 v100, v101, 2, v100
	v_lshl_or_b32 v100, v45, 5, v100
	global_load_dword v98, v100, s[14:15]
	v_lshlrev_b32_e32 v99, 7, v45
	buffer_load_dwordx4 v[106:109], v106, s[76:79], 0 offen sc1
	buffer_load_dwordx4 v[110:113], v110, s[76:79], 0 offen sc1
	buffer_load_dwordx4 v[114:117], v114, s[76:79], 0 offen sc1
	buffer_load_dwordx4 v[118:121], v118, s[76:79], 0 offen sc1
	buffer_load_dwordx4 v[122:125], v122, s[76:79], 0 offen sc1
	buffer_load_dwordx4 v[126:129], v126, s[76:79], 0 offen sc1
	buffer_load_dwordx4 v[130:133], v130, s[76:79], 0 offen sc1
	buffer_load_dwordx4 v[134:137], v134, s[76:79], 0 offen sc1
	s_movk_i32 s11, 0x210
	v_mul_lo_u32 v218, v44, s11
	v_mul_lo_u32 v219, v46, s11
	v_mul_lo_u32 v220, v48, s11
	v_mul_lo_u32 v221, v50, s11
	v_readlane_b32 s11, v254, 25
	v_lshl_add_u64 v[206:207], v[40:41], 2, s[20:21]
	v_lshlrev_b32_e32 v193, 2, v45
	v_add_u32_e32 v231, 0, v49
	v_mov_b32_e32 v41, v97
	v_mov_b32_e32 v44, v97
	v_mov_b32_e32 v46, v97
	s_mov_b32 s4, 0
	s_or_b32 s5, s3, 31
	v_mov_b32_e32 v234, 0
	s_waitcnt vmcnt(12)
	v_lshlrev_b32_e32 v86, 16, v3
	v_and_b32_e32 v87, 0xffff0000, v3
	v_lshlrev_b32_e32 v92, 16, v1
	s_waitcnt vmcnt(8)
	ds_bpermute_b32 v32, v99, v98
	v_add_u32_e32 v99, 4, v99
	ds_bpermute_b32 v33, v99, v98
	v_add_u32_e32 v99, 4, v99
	ds_bpermute_b32 v34, v99, v98
	v_add_u32_e32 v99, 4, v99
	ds_bpermute_b32 v35, v99, v98
	v_add_u32_e32 v99, 4, v99
	ds_bpermute_b32 v28, v99, v98
	v_add_u32_e32 v99, 4, v99
	ds_bpermute_b32 v29, v99, v98
	v_add_u32_e32 v99, 4, v99
	ds_bpermute_b32 v30, v99, v98
	v_add_u32_e32 v99, 4, v99
	ds_bpermute_b32 v31, v99, v98
	v_add_u32_e32 v99, 4, v99
	s_waitcnt lgkmcnt(4)
	ds_bpermute_b32 v24, v99, v98
	v_add_u32_e32 v99, 4, v99
	ds_bpermute_b32 v25, v99, v98
	v_add_u32_e32 v99, 4, v99
	ds_bpermute_b32 v26, v99, v98
	v_add_u32_e32 v99, 4, v99
	ds_bpermute_b32 v27, v99, v98
	v_add_u32_e32 v99, 4, v99
	ds_bpermute_b32 v20, v99, v98
	v_add_u32_e32 v99, 4, v99
	ds_bpermute_b32 v21, v99, v98
	v_add_u32_e32 v99, 4, v99
	ds_bpermute_b32 v22, v99, v98
	v_add_u32_e32 v99, 4, v99
	ds_bpermute_b32 v23, v99, v98
	v_add_u32_e32 v99, 4, v99
	s_waitcnt lgkmcnt(4)
	ds_bpermute_b32 v16, v99, v98
	v_add_u32_e32 v99, 4, v99
	ds_bpermute_b32 v17, v99, v98
	v_add_u32_e32 v99, 4, v99
	ds_bpermute_b32 v18, v99, v98
	v_add_u32_e32 v99, 4, v99
	ds_bpermute_b32 v19, v99, v98
	v_add_u32_e32 v99, 4, v99
	ds_bpermute_b32 v12, v99, v98
	v_add_u32_e32 v99, 4, v99
	ds_bpermute_b32 v13, v99, v98
	v_add_u32_e32 v99, 4, v99
	ds_bpermute_b32 v14, v99, v98
	v_add_u32_e32 v99, 4, v99
	ds_bpermute_b32 v15, v99, v98
	v_add_u32_e32 v99, 4, v99
	s_waitcnt lgkmcnt(4)
	ds_bpermute_b32 v8, v99, v98
	v_add_u32_e32 v99, 4, v99
	ds_bpermute_b32 v9, v99, v98
	v_add_u32_e32 v99, 4, v99
	ds_bpermute_b32 v10, v99, v98
	v_add_u32_e32 v99, 4, v99
	ds_bpermute_b32 v11, v99, v98
	v_add_u32_e32 v99, 4, v99
	ds_bpermute_b32 v4, v99, v98
	v_add_u32_e32 v99, 4, v99
	ds_bpermute_b32 v5, v99, v98
	v_add_u32_e32 v99, 4, v99
	ds_bpermute_b32 v6, v99, v98
	v_add_u32_e32 v99, 4, v99
	ds_bpermute_b32 v7, v99, v98
	v_and_b32_e32 v53, 0xffff0000, v65
	v_and_b32_e32 v55, 0xffff0000, v64
	v_lshlrev_b32_e32 v52, 16, v65
	v_lshlrev_b32_e32 v54, 16, v64
	v_mov_b32_e32 v58, v53
	v_mov_b32_e32 v59, v55
	v_mov_b32_e32 v56, v52
	v_mov_b32_e32 v57, v54
	v_pk_mul_f32 v[58:59], v[58:59], v[58:59]
	v_and_b32_e32 v93, 0xffff0000, v1
	v_pk_fma_f32 v[60:61], v[56:57], v[56:57], v[58:59]
	v_and_b32_e32 v57, 0xffff0000, v63
	v_and_b32_e32 v59, 0xffff0000, v62
	v_lshlrev_b32_e32 v56, 16, v63
	v_lshlrev_b32_e32 v58, 16, v62
	v_mov_b32_e32 v64, v57
	v_mov_b32_e32 v65, v59
	v_mov_b32_e32 v62, v56
	v_mov_b32_e32 v63, v58
	v_pk_mul_f32 v[64:65], v[64:65], v[64:65]
	v_lshlrev_b32_e32 v138, 16, v0
	v_pk_fma_f32 v[66:67], v[62:63], v[62:63], v[64:65]
	v_and_b32_e32 v63, 0xffff0000, v77
	v_and_b32_e32 v65, 0xffff0000, v76
	v_lshlrev_b32_e32 v62, 16, v77
	v_lshlrev_b32_e32 v64, 16, v76
	v_mov_b32_e32 v70, v63
	v_mov_b32_e32 v71, v65
	v_mov_b32_e32 v68, v62
	v_mov_b32_e32 v69, v64
	v_pk_mul_f32 v[70:71], v[70:71], v[70:71]
	v_and_b32_e32 v139, 0xffff0000, v0
	v_pk_fma_f32 v[72:73], v[68:69], v[68:69], v[70:71]
	v_and_b32_e32 v69, 0xffff0000, v75
	v_and_b32_e32 v71, 0xffff0000, v74
	v_lshlrev_b32_e32 v68, 16, v75
	v_lshlrev_b32_e32 v70, 16, v74
	v_mov_b32_e32 v76, v69
	v_mov_b32_e32 v77, v71
	v_mov_b32_e32 v74, v68
	v_mov_b32_e32 v75, v70
	v_pk_mul_f32 v[76:77], v[76:77], v[76:77]
	v_and_b32_e32 v79, 0xffff0000, v38
	v_pk_fma_f32 v[76:77], v[74:75], v[74:75], v[76:77]
	v_and_b32_e32 v75, 0xffff0000, v39
	v_pk_mul_f32 v[88:89], v[86:87], v[86:87]
	v_lshlrev_b32_e32 v90, 16, v2
	v_and_b32_e32 v91, 0xffff0000, v2
	v_pk_mul_f32 v[94:95], v[92:93], v[92:93]
	v_pk_mul_f32 v[0:1], v[138:139], v[138:139]
	v_lshlrev_b32_e32 v74, 16, v39
	v_lshlrev_b32_e32 v78, 16, v38
	v_mov_b32_e32 v80, v75
	v_mov_b32_e32 v81, v79
	v_pk_mul_f32 v[2:3], v[90:91], v[90:91]
	v_add_f32_e32 v88, v88, v89
	v_add_f32_e32 v89, v94, v95
	v_add_f32_e32 v0, v0, v1
	v_mov_b32_e32 v38, v74
	v_mov_b32_e32 v39, v78
	v_pk_mul_f32 v[80:81], v[80:81], v[80:81]
	v_lshlrev_b32_e32 v84, 16, v36
	v_and_b32_e32 v85, 0xffff0000, v36
	v_add_f32_e32 v0, v0, v89
	v_add_f32_e32 v1, v2, v3
	v_pk_fma_f32 v[38:39], v[38:39], v[38:39], v[80:81]
	v_lshlrev_b32_e32 v80, 16, v37
	v_and_b32_e32 v81, 0xffff0000, v37
	v_pk_mul_f32 v[36:37], v[84:85], v[84:85]
	v_add_f32_e32 v0, v1, v0
	v_pk_mul_f32 v[82:83], v[80:81], v[80:81]
	v_add_f32_e32 v0, v88, v0
	v_add_f32_e32 v1, v36, v37
	v_add_f32_e32 v0, v1, v0
	v_add_f32_e32 v1, v82, v83
	v_add_f32_e32 v0, v1, v0
	v_add_f32_e32 v0, v39, v0
	v_add_f32_e32 v0, v38, v0
	v_add_f32_e32 v0, v77, v0
	v_add_f32_e32 v0, v76, v0
	v_add_f32_e32 v0, v73, v0
	v_add_f32_e32 v0, v72, v0
	v_add_f32_e32 v0, v67, v0
	v_add_f32_e32 v0, v66, v0
	v_add_f32_e32 v0, v61, v0
	v_add_f32_e32 v0, v60, v0
	ds_bpermute_b32 v1, v140, v0
	v_mov_b32_e32 v36, v97
	v_mov_b32_e32 v37, v97
	v_mov_b32_e32 v38, v97
	v_mov_b32_e32 v39, v97
	s_waitcnt lgkmcnt(0)
	v_add_f32_e32 v0, v0, v1
	v_fmamk_f32 v0, v0, 0x3c800000, v225
	v_cmp_gt_f32_e32 vcc, s30, v0
	v_mul_f32_e32 v1, 0x4b800000, v0
	s_nop 0
	v_cndmask_b32_e32 v0, v0, v1, vcc
	v_rsq_f32_e32 v0, v0
	s_nop 0
	v_mul_f32_e32 v1, 0x45800000, v0
	v_cndmask_b32_e32 v0, v0, v1, vcc
	v_mul_f32_e32 v0, 0x3e38aa3b, v0
	v_pk_mul_f32 v[2:3], v[0:1], v[138:139] op_sel_hi:[0,1]
	s_waitcnt lgkmcnt(0)
	v_pk_mul_f32 v[2:3], v[32:33], v[2:3]
	v_mov_b32_e32 v32, v97
	v_cvt_pk_bf16_f32 v138, v2, v3
	v_pk_mul_f32 v[2:3], v[0:1], v[92:93] op_sel_hi:[0,1]
	v_pk_mul_f32 v[2:3], v[34:35], v[2:3]
	v_mov_b32_e32 v33, v97
	v_cvt_pk_bf16_f32 v139, v2, v3
	v_pk_mul_f32 v[2:3], v[0:1], v[90:91] op_sel_hi:[0,1]
	v_pk_mul_f32 v[2:3], v[28:29], v[2:3]
	v_mov_b32_e32 v34, v97
	v_cvt_pk_bf16_f32 v140, v2, v3
	v_pk_mul_f32 v[2:3], v[0:1], v[86:87] op_sel_hi:[0,1]
	v_pk_mul_f32 v[2:3], v[30:31], v[2:3]
	v_mov_b32_e32 v35, v97
	v_cvt_pk_bf16_f32 v141, v2, v3
	v_pk_mul_f32 v[2:3], v[0:1], v[84:85] op_sel_hi:[0,1]
	s_nop 0
	v_pk_mul_f32 v[2:3], v[24:25], v[2:3]
	s_nop 0
	v_cvt_pk_bf16_f32 v142, v2, v3
	v_pk_mul_f32 v[2:3], v[0:1], v[80:81] op_sel_hi:[0,1]
	v_pk_mul_f32 v[2:3], v[26:27], v[2:3]
	s_nop 0
	v_cvt_pk_bf16_f32 v143, v2, v3
	v_pk_mul_f32 v[2:3], v[0:1], v[78:79] op_sel_hi:[0,1]
	v_pk_mul_f32 v[2:3], v[20:21], v[2:3]
	s_nop 0
	v_cvt_pk_bf16_f32 v144, v2, v3
	v_pk_mul_f32 v[2:3], v[0:1], v[74:75] op_sel_hi:[0,1]
	v_pk_mul_f32 v[2:3], v[22:23], v[2:3]
	s_nop 0
	v_cvt_pk_bf16_f32 v145, v2, v3
	v_pk_mul_f32 v[2:3], v[0:1], v[70:71] op_sel_hi:[0,1]
	s_nop 0
	v_pk_mul_f32 v[2:3], v[16:17], v[2:3]
	v_xor_b32_e32 v16, 1, v227
	v_cvt_pk_bf16_f32 v146, v2, v3
	v_pk_mul_f32 v[2:3], v[0:1], v[68:69] op_sel_hi:[0,1]
	v_pk_mul_f32 v[2:3], v[18:19], v[2:3]
	v_cmp_lt_i32_e32 vcc, v16, v51
	v_cvt_pk_bf16_f32 v147, v2, v3
	v_pk_mul_f32 v[2:3], v[0:1], v[64:65] op_sel_hi:[0,1]
	v_pk_mul_f32 v[2:3], v[12:13], v[2:3]
	v_cndmask_b32_e32 v16, v227, v16, vcc
	v_cvt_pk_bf16_f32 v148, v2, v3
	v_pk_mul_f32 v[2:3], v[0:1], v[62:63] op_sel_hi:[0,1]
	v_pk_mul_f32 v[2:3], v[14:15], v[2:3]
	v_lshlrev_b32_e32 v191, 2, v16
	v_cvt_pk_bf16_f32 v149, v2, v3
	v_pk_mul_f32 v[2:3], v[0:1], v[58:59] op_sel_hi:[0,1]
	s_nop 0
	v_pk_mul_f32 v[2:3], v[8:9], v[2:3]
	v_xor_b32_e32 v16, 2, v227
	v_cvt_pk_bf16_f32 v150, v2, v3
	v_pk_mul_f32 v[2:3], v[0:1], v[56:57] op_sel_hi:[0,1]
	v_pk_mul_f32 v[2:3], v[10:11], v[2:3]
	v_cmp_lt_i32_e32 vcc, v16, v51
	v_cvt_pk_bf16_f32 v151, v2, v3
	v_pk_mul_f32 v[2:3], v[0:1], v[54:55] op_sel_hi:[0,1]
	v_pk_mul_f32 v[0:1], v[0:1], v[52:53] op_sel_hi:[0,1]
	v_pk_mul_f32 v[0:1], v[6:7], v[0:1]
	v_cndmask_b32_e32 v16, v227, v16, vcc
	v_cvt_pk_bf16_f32 v153, v0, v1
	s_nop 0
	v_mov_b32_e32 v0, v237
	v_lshlrev_b32_e32 v195, 2, v16
	v_xor_b32_e32 v16, 4, v227
	v_cmp_lt_i32_e32 vcc, v16, v51
	v_mov_b32_e32 v17, v97
	v_pk_mul_f32 v[2:3], v[4:5], v[2:3]
	v_cndmask_b32_e32 v16, v227, v16, vcc
	v_lshlrev_b32_e32 v197, 2, v16
	v_lshlrev_b32_e32 v16, 4, v40
	v_and_b32_e32 v199, 0x1f0, v16
	v_lshlrev_b32_e32 v16, 1, v43
	v_lshl_add_u64 v[204:205], s[12:13], 0, v[16:17]
	v_mul_u32_u24_e32 v17, 0x210, v47
	v_lshl_or_b32 v17, v45, 3, v17
	v_mul_u32_u24_e32 v16, 0x90, v47
	v_add_u32_e32 v232, s11, v17
	v_readlane_b32 s11, v254, 26
	v_cvt_pk_bf16_f32 v152, v2, v3
	v_lshlrev_b32_e32 v203, 2, v40
	v_mul_lo_u32 v205, v42, s93
	v_add3_u32 v233, v16, v49, s11
	v_mov_b32_e32 v40, v97
	v_mov_b32_e32 v42, v97
	v_mov_b32_e32 v43, v97
	v_mov_b32_e32 v45, v97
	v_mov_b32_e32 v47, v97
	v_mov_b64_e32 v[16:17], v[32:33]
	s_mov_b64 s[20:21], -1
	v_mov_b64_e32 v[18:19], v[34:35]
	v_mov_b64_e32 v[20:21], v[36:37]
	v_mov_b64_e32 v[22:23], v[38:39]
	v_mov_b64_e32 v[24:25], v[40:41]
	v_mov_b64_e32 v[26:27], v[42:43]
	v_mov_b64_e32 v[28:29], v[44:45]
	v_mov_b64_e32 v[30:31], v[46:47]
	s_waitcnt vmcnt(0)
	v_mov_b32_e32 v14, v0
	v_mov_b32_e32 v15, v0
	v_mov_b32_e32 v1, v0
	v_mov_b32_e32 v2, v0
	v_mov_b32_e32 v3, v0
	v_mov_b32_e32 v4, v0
	v_mov_b32_e32 v5, v0
	v_mov_b32_e32 v6, v0
	v_mov_b32_e32 v7, v0
	v_mov_b32_e32 v8, v0
	v_mov_b32_e32 v9, v0
	v_mov_b32_e32 v10, v0
	v_mov_b32_e32 v11, v0
	v_mov_b32_e32 v12, v0
	v_mov_b32_e32 v13, v0
	v_mov_b64_e32 v[62:63], v[14:15]
	v_mov_b64_e32 v[60:61], v[12:13]
	v_mov_b64_e32 v[58:59], v[10:11]
	v_mov_b64_e32 v[56:57], v[8:9]
	v_mov_b64_e32 v[54:55], v[6:7]
	v_mov_b64_e32 v[52:53], v[4:5]
	v_mov_b64_e32 v[50:51], v[2:3]
	v_mov_b64_e32 v[48:49], v[0:1]
	s_branch .LBB0_148
